# wave all-reduces of mn1, mn2 and the M2 table quantisation: six ds_bpermute rounds replaced by DPP row rotations + permlane swaps
# speedup vs baseline: 1.0078x; 1.0078x over previous
; __device__ __forceinline__ float bf_lo(unsigned u) { return __uint_as_float(u << 16); }
; __device__ __forceinline__ float bf_hi(unsigned u) { return __uint_as_float(u & 0xffff0000u); }
; __device__ __forceinline__ int vblk() { return (int)blockIdx.x * 2 + half_id(); }
; __device__ __forceinline__ int vgrid() { return (int)gridDim.x * 2; }
; __device__ void phase_modnorm(const Params& p, const float* __restrict__ src, const bf16_t* __restrict__ srcb, const float* __restrict__ g, int shift_idx, int scale_idx, bf16_t* __restrict__ dst) {
;     ...
;     for (int tok = vblk() * 4 + wave; tok < NTOK; tok += vgrid() * 4) {
;         const int b = tok >> 11;
;         const float* xr = src + (size_t)tok * DM;
;         f32x4 v[4];
;         float ss = 0.f;
; #pragma unroll
;         for (int c = 0; c < 4; c++) {
;             if (srcb) {
;                 const u32x2 w = *(const u32x2*)(srcb + (size_t)tok * DM + c * 256 + lane * 4);
;                 v[c] = (f32x4){bf_lo(w.x), bf_hi(w.x), bf_lo(w.y), bf_hi(w.y)};
;             } else v[c] = *(const f32x4*)(xr + c * 256 + lane * 4);
;             ss += v[c][0] * v[c][0] + v[c][1] * v[c][1] + v[c][2] * v[c][2] + v[c][3] * v[c][3];
;         }
;         ss = wave_sum(ss);
;         const float rstd = rsqrtf(ss * (1.f / 1024.f) + 1e-6f);
; #pragma unroll
;         for (int c = 0; c < 4; c++) {
;             const int d = c * 256 + lane * 4;
;             const f32x4 gg = *(const f32x4*)(g + d);
;             const f32x4 sc = *(const f32x4*)(mod + b * 6144 + scale_idx * 1024 + d);
;             const f32x4 sh = *(const f32x4*)(mod + b * 6144 + shift_idx * 1024 + d);
;             float o[4];
; #pragma unroll
;             for (int j = 0; j < 4; j++) o[j] = (v[c][j] * rstd) * gg[j] * (1.f + sc[j]) + sh[j];
;             *(u32x2*)(dst + (size_t)tok * DM + d) = (u32x2){pack2(o[0], o[1]), pack2(o[2], o[3])};
;         }
;     }
.LBB0_236:
	global_load_dwordx4 v[38:41], v[22:23], off offset:-3072
	global_load_dwordx4 v[42:45], v[22:23], off offset:-2048
	global_load_dwordx4 v[46:49], v[22:23], off offset:-1024
	global_load_dwordx4 v[50:53], v[22:23], off
	v_ashrrev_i32_e32 v37, 11, v16
	v_mul_i32_i24_e32 v54, 0x1800, v37
	v_ashrrev_i32_e32 v55, 31, v54
	v_lshl_add_u64 v[54:55], v[54:55], 2, s[6:7]
	v_lshl_add_u64 v[62:63], v[54:55], 0, s[18:19]
	v_lshl_add_u64 v[86:87], v[54:55], 0, v[18:19]
	v_lshl_add_u64 v[88:89], v[62:63], 0, v[18:19]
	v_lshl_add_u64 v[90:91], v[62:63], 0, v[24:25]
	v_lshl_add_u64 v[92:93], v[62:63], 0, v[26:27]
	global_load_dwordx4 v[54:57], v[86:87], off offset:1024
	global_load_dwordx4 v[58:61], v[86:87], off offset:2048
	v_lshl_add_u64 v[94:95], v[62:63], 0, v[28:29]
	global_load_dwordx4 v[62:65], v[88:89], off
	global_load_dwordx4 v[66:69], v[90:91], off
	global_load_dwordx4 v[70:73], v[92:93], off
	global_load_dwordx4 v[74:77], v[94:95], off
	global_load_dwordx4 v[78:81], v[86:87], off
	global_load_dwordx4 v[82:85], v[86:87], off offset:3072
	v_add_u32_e32 v16, s8, v16
	v_cmp_lt_i32_e32 vcc, s1, v16
	s_or_b64 s[16:17], vcc, s[16:17]
	v_lshl_add_u64 v[22:23], v[22:23], 0, s[14:15]
	s_waitcnt vmcnt(11)
	v_mov_b32_e32 v88, v39
	s_waitcnt vmcnt(10)
	v_mov_b32_e32 v89, v43
	v_mov_b32_e32 v86, v38
	v_mov_b32_e32 v87, v42
	s_waitcnt vmcnt(9)
	v_mov_b32_e32 v96, v47
	s_waitcnt vmcnt(8)
	v_mov_b32_e32 v97, v51
	v_pk_mul_f32 v[88:89], v[88:89], v[88:89]
	v_mov_b32_e32 v90, v40
	v_mov_b32_e32 v91, v44
	v_mov_b32_e32 v94, v46
	v_mov_b32_e32 v95, v50
	v_pk_mul_f32 v[96:97], v[96:97], v[96:97]
	v_pk_fma_f32 v[86:87], v[86:87], v[86:87], v[88:89]
	v_mov_b32_e32 v92, v41
	v_mov_b32_e32 v93, v45
	v_mov_b32_e32 v98, v48
	v_mov_b32_e32 v99, v52
	v_pk_fma_f32 v[88:89], v[94:95], v[94:95], v[96:97]
	v_pk_fma_f32 v[86:87], v[90:91], v[90:91], v[86:87]
	v_mov_b32_e32 v100, v49
	v_mov_b32_e32 v101, v53
	v_pk_fma_f32 v[88:89], v[98:99], v[98:99], v[88:89]
	v_pk_fma_f32 v[86:87], v[92:93], v[92:93], v[86:87]
	v_pk_fma_f32 v[88:89], v[100:101], v[100:101], v[88:89]
	v_add_f32_e32 v37, v86, v87
	v_add_f32_e32 v37, v37, v88
	v_add_f32_e32 v37, v37, v89
	s_nop 1
	v_add_f32_dpp v37, v37, v37 row_ror:8 row_mask:0xf bank_mask:0xf
	s_nop 1
	v_add_f32_dpp v37, v37, v37 row_ror:4 row_mask:0xf bank_mask:0xf
	s_nop 1
	v_add_f32_dpp v37, v37, v37 row_ror:2 row_mask:0xf bank_mask:0xf
	s_nop 1
	v_add_f32_dpp v37, v37, v37 row_ror:1 row_mask:0xf bank_mask:0xf
	v_mov_b32_e32 v86, v37
	s_nop 1
	v_permlane16_swap_b32_e32 v37, v86
	v_add_f32_e32 v37, v37, v86
	v_mov_b32_e32 v86, v37
	s_nop 1
	v_permlane32_swap_b32_e32 v37, v86
	v_add_f32_e32 v37, v37, v86
	s_waitcnt vmcnt(5)
	v_pk_add_f32 v[62:63], v[62:63], 1.0 op_sel_hi:[1,0]
	v_pk_add_f32 v[64:65], v[64:65], 1.0 op_sel_hi:[1,0]
	s_waitcnt vmcnt(4)
	v_pk_add_f32 v[66:67], v[66:67], 1.0 op_sel_hi:[1,0]
	v_pk_add_f32 v[68:69], v[68:69], 1.0 op_sel_hi:[1,0]
	s_waitcnt vmcnt(3)
	v_pk_add_f32 v[70:71], v[70:71], 1.0 op_sel_hi:[1,0]
	v_pk_add_f32 v[72:73], v[72:73], 1.0 op_sel_hi:[1,0]
	s_waitcnt vmcnt(2)
	v_pk_add_f32 v[74:75], v[74:75], 1.0 op_sel_hi:[1,0]
	v_pk_add_f32 v[76:77], v[76:77], 1.0 op_sel_hi:[1,0]
	v_fmamk_f32 v37, v37, 0x3a800000, v17
	v_mul_f32_e32 v86, 0x4b800000, v37
	v_cmp_gt_f32_e32 vcc, s0, v37
	s_nop 1
	v_cndmask_b32_e32 v37, v37, v86, vcc
	v_rsq_f32_e32 v37, v37
	s_nop 0
	v_mul_f32_e32 v86, 0x45800000, v37
	v_cndmask_b32_e32 v86, v37, v86, vcc
	v_pk_mul_f32 v[38:39], v[38:39], v[86:87] op_sel_hi:[1,0]
	v_pk_mul_f32 v[40:41], v[40:41], v[86:87] op_sel_hi:[1,0]
	v_pk_mul_f32 v[42:43], v[42:43], v[86:87] op_sel_hi:[1,0]
	v_pk_mul_f32 v[44:45], v[44:45], v[86:87] op_sel_hi:[1,0]
	v_pk_mul_f32 v[46:47], v[46:47], v[86:87] op_sel_hi:[1,0]
	v_pk_mul_f32 v[48:49], v[48:49], v[86:87] op_sel_hi:[1,0]
	v_pk_mul_f32 v[50:51], v[50:51], v[86:87] op_sel_hi:[1,0]
	v_pk_mul_f32 v[52:53], v[52:53], v[86:87] op_sel_hi:[1,0]
	v_pk_mul_f32 v[38:39], v[0:1], v[38:39]
	v_pk_mul_f32 v[40:41], v[2:3], v[40:41]
	v_pk_mul_f32 v[42:43], v[4:5], v[42:43]
	v_pk_mul_f32 v[44:45], v[6:7], v[44:45]
	v_pk_mul_f32 v[46:47], v[8:9], v[46:47]
	v_pk_mul_f32 v[48:49], v[10:11], v[48:49]
	v_pk_mul_f32 v[50:51], v[12:13], v[50:51]
	v_pk_mul_f32 v[52:53], v[14:15], v[52:53]
	s_waitcnt vmcnt(1)
	v_pk_fma_f32 v[38:39], v[62:63], v[38:39], v[78:79]
	v_pk_fma_f32 v[40:41], v[64:65], v[40:41], v[80:81]
	v_pk_fma_f32 v[42:43], v[66:67], v[42:43], v[54:55]
	v_pk_fma_f32 v[44:45], v[68:69], v[44:45], v[56:57]
	v_pk_fma_f32 v[46:47], v[70:71], v[46:47], v[58:59]
	v_pk_fma_f32 v[48:49], v[72:73], v[48:49], v[60:61]
	s_waitcnt vmcnt(0)
	v_pk_fma_f32 v[50:51], v[74:75], v[50:51], v[82:83]
	v_pk_fma_f32 v[52:53], v[76:77], v[52:53], v[84:85]
	v_cvt_pk_bf16_f32 v38, v38, v39
	v_cvt_pk_bf16_f32 v39, v40, v41
	v_cvt_pk_bf16_f32 v40, v42, v43
	v_cvt_pk_bf16_f32 v41, v44, v45
	v_cvt_pk_bf16_f32 v42, v46, v47
	v_cvt_pk_bf16_f32 v43, v48, v49
	v_cvt_pk_bf16_f32 v44, v50, v51
	v_cvt_pk_bf16_f32 v45, v52, v53
	global_store_dwordx2 v[20:21], v[38:39], off
	global_store_dwordx2 v[20:21], v[40:41], off offset:512
	global_store_dwordx2 v[20:21], v[42:43], off offset:1024
	global_store_dwordx2 v[20:21], v[44:45], off offset:1536
	v_lshl_add_u64 v[20:21], v[20:21], 0, s[10:11]
	s_andn2_b64 exec, exec, s[16:17]
	s_cbranch_execnz .LBB0_236

; __device__ __forceinline__ int vblk() { return (int)blockIdx.x * 2 + half_id(); }
; __device__ __forceinline__ int vgrid() { return (int)gridDim.x * 2; }
; __device__ __forceinline__ float wave_max(float v) {
; #pragma unroll
;     for (int o = 32; o > 0; o >>= 1) v = fmaxf(v, __shfl_xor(v, o, 64));
;     return v;
; }
; __device__ void phaseM2(const Params& p, char* lds) {
;     ...
;         for (int row = vblk() * 4 + wave; row < 32768; row += vgrid() * 4) {
;             const bool isv = row >= 16384;
;             const float* srcp = (isv ? p.peer_v : p.peer_u) + (size_t)(row & 16383) * DM + lane * 16;
;             f32x4 a[4];
;             float mx = 0.f;
; #pragma unroll
;             for (int i = 0; i < 4; i++) {
;                 a[i] = *(const f32x4*)(srcp + i * 4);
;                 mx = fmaxf(mx, fmaxf(fmaxf(fabsf(a[i][0]), fabsf(a[i][1])), fmaxf(fabsf(a[i][2]), fabsf(a[i][3]))));
;             }
;             mx = wave_max(mx);
;             if (isv) {
.LBB0_794:
	v_cmp_lt_i32_e32 vcc, s15, v16
	v_and_b32_e32 v2, 0xfffc00, v32
	s_nop 0
	v_cndmask_b32_e32 v18, v33, v34, vcc
	v_lshl_add_u64 v[0:1], s[8:9], 0, v[18:19]
	global_load_dwordx2 v[0:1], v[0:1], off
	v_lshlrev_b32_e32 v18, 2, v2
	v_cmp_gt_i32_e32 vcc, s3, v16
	s_waitcnt vmcnt(0)
	v_lshl_add_u64 v[0:1], v[0:1], 0, v[18:19]
	v_lshl_add_u64 v[36:37], v[0:1], 0, v[24:25]
	global_load_dwordx4 v[12:15], v[36:37], off
	global_load_dwordx4 v[8:11], v[36:37], off offset:16
	global_load_dwordx4 v[4:7], v[36:37], off offset:32
	global_load_dwordx4 v[0:3], v[36:37], off offset:48
	s_waitcnt vmcnt(3)
	v_max_f32_e64 v18, |v15|, |v15|
	v_max_f32_e64 v36, |v14|, |v14|
	s_waitcnt vmcnt(2)
	v_max_f32_e64 v37, |v11|, |v11|
	v_max_f32_e64 v38, |v10|, |v10|
	s_waitcnt vmcnt(1)
	v_max_f32_e64 v39, |v7|, |v7|
	v_max_f32_e64 v40, |v6|, |v6|
	s_waitcnt vmcnt(0)
	v_max_f32_e64 v41, |v3|, |v3|
	v_max_f32_e64 v42, |v2|, |v2|
	v_max_f32_e32 v18, v36, v18
	v_max_f32_e32 v36, v38, v37
	v_max_f32_e32 v37, v40, v39
	v_max_f32_e32 v38, v42, v41
	v_max3_f32 v18, |v12|, |v13|, v18
	v_max3_f32 v36, |v8|, |v9|, v36
	v_max3_f32 v37, |v4|, |v5|, v37
	v_max3_f32 v18, v18, 0, v36
	v_max3_f32 v36, |v0|, |v1|, v38
	v_max3_f32 v18, v18, v37, v36
	s_nop 1
	v_max_f32_dpp v18, v18, v18 row_ror:8 row_mask:0xf bank_mask:0xf
	s_nop 1
	v_max_f32_dpp v18, v18, v18 row_ror:4 row_mask:0xf bank_mask:0xf
	s_nop 1
	v_max_f32_dpp v18, v18, v18 row_ror:2 row_mask:0xf bank_mask:0xf
	s_nop 1
	v_max_f32_dpp v18, v18, v18 row_ror:1 row_mask:0xf bank_mask:0xf
	v_mov_b32_e32 v36, v18
	s_nop 1
	v_permlane16_swap_b32_e32 v18, v36
	v_max_f32_e32 v18, v18, v36
	v_mov_b32_e32 v36, v18
	s_nop 1
	v_permlane32_swap_b32_e32 v18, v36
	v_max_f32_e32 v36, v18, v36
	s_and_saveexec_b64 s[6:7], vcc
	s_xor_b64 s[20:21], exec, s[6:7]
	s_cbranch_execz .LBB0_798
; __device__ void phaseM2(const Params& p, char* lds) {
;     ...
;                 float ssq = 0.f;
; #pragma unroll
;                 for (int i = 0; i < 4; i++) ssq += a[i][0] * a[i][0] + a[i][1] * a[i][1] + a[i][2] * a[i][2] + a[i][3] * a[i][3];
;                 ssq = wave_sum(ssq);
;                 mx = fminf(mx, 2.4f * sqrtf(ssq * (1.f / 1024.f)));
;                 const float inv = mx > 0.f ? 7.f / mx : 0.f;
;                 unsigned w2[2] = {0u, 0u};
; #pragma unroll
;                 for (int i = 0; i < 4; i++)
; #pragma unroll
;                     for (int j = 0; j < 4; j++) {
;                         const int e = i * 4 + j;
;                         int qi = (int)rintf(a[i][j] * inv);
;                         qi = qi > 7 ? 7 : (qi < -7 ? -7 : qi);
;                         w2[e >> 3] |= (unsigned)(qi & 15) << ((e & 7) * 4);
;                     }
;                 *(u32x2*)(tq + (size_t)row * 512 + lane * 8) = (u32x2){w2[0], w2[1]};
;                 if (lane == 0) tsc[2 * row] = mx * (1.f / 7.f);
;             }
	v_mul_f32_e32 v18, v13, v13
	v_mul_f32_e32 v37, v9, v9
	v_mov_b32_e32 v40, v5
	v_mov_b32_e32 v41, v1
	v_fmac_f32_e32 v18, v12, v12
	v_fmac_f32_e32 v37, v8, v8
	v_mov_b32_e32 v38, v4
	v_mov_b32_e32 v39, v0
	v_pk_mul_f32 v[40:41], v[40:41], v[40:41]
	v_fmac_f32_e32 v18, v14, v14
	v_fmac_f32_e32 v37, v10, v10
	v_mov_b32_e32 v42, v6
	v_mov_b32_e32 v43, v2
	v_pk_fma_f32 v[38:39], v[38:39], v[38:39], v[40:41]
	v_fmac_f32_e32 v18, v15, v15
	v_fmac_f32_e32 v37, v11, v11
	v_mov_b32_e32 v44, v7
	v_mov_b32_e32 v45, v3
	v_pk_fma_f32 v[38:39], v[42:43], v[42:43], v[38:39]
	v_add_f32_e32 v18, v18, v37
	v_pk_fma_f32 v[38:39], v[44:45], v[44:45], v[38:39]
	v_max_f32_e32 v36, v36, v36
	v_add_f32_e32 v18, v18, v38
	v_add_f32_e32 v18, v18, v39
	s_nop 1
	v_add_f32_dpp v18, v18, v18 row_ror:8 row_mask:0xf bank_mask:0xf
	s_nop 1
	v_add_f32_dpp v18, v18, v18 row_ror:4 row_mask:0xf bank_mask:0xf
	s_nop 1
	v_add_f32_dpp v18, v18, v18 row_ror:2 row_mask:0xf bank_mask:0xf
	s_nop 1
	v_add_f32_dpp v18, v18, v18 row_ror:1 row_mask:0xf bank_mask:0xf
	v_mov_b32_e32 v37, v18
	s_nop 1
	v_permlane16_swap_b32_e32 v18, v37
	v_add_f32_e32 v18, v18, v37
	v_mov_b32_e32 v37, v18
	s_nop 1
	v_permlane32_swap_b32_e32 v18, v37
	v_add_f32_e32 v18, v18, v37
	v_mul_f32_e32 v18, 0x3a800000, v18
	v_mul_f32_e32 v37, 0x4f800000, v18
	v_cmp_gt_f32_e32 vcc, s22, v18
	s_nop 1
	v_cndmask_b32_e32 v18, v18, v37, vcc
	v_sqrt_f32_e32 v37, v18
	s_nop 0
	v_add_u32_e32 v38, -1, v37
	v_add_u32_e32 v39, 1, v37
	v_fma_f32 v40, -v38, v37, v18
	v_fma_f32 v41, -v39, v37, v18
	v_cmp_ge_f32_e64 s[6:7], 0, v40
	s_nop 1
	v_cndmask_b32_e64 v37, v37, v38, s[6:7]
	v_cmp_lt_f32_e64 s[6:7], 0, v41
	s_nop 1
	v_cndmask_b32_e64 v37, v37, v39, s[6:7]
	v_mul_f32_e32 v38, 0x37800000, v37
	v_cndmask_b32_e32 v37, v37, v38, vcc
	v_cmp_class_f32_e32 vcc, v18, v35
	s_nop 1
	v_cndmask_b32_e32 v18, v37, v18, vcc
	v_mul_f32_e32 v18, 0x4019999a, v18
	v_min_f32_e32 v18, v36, v18
	v_div_scale_f32 v36, s[6:7], v18, v18, s23
	v_rcp_f32_e32 v37, v36
	v_div_scale_f32 v38, vcc, s23, v18, s23
	v_fma_f32 v39, -v36, v37, 1.0
	v_fmac_f32_e32 v37, v39, v37
	v_mul_f32_e32 v39, v38, v37
	v_fma_f32 v40, -v36, v39, v38
	v_fmac_f32_e32 v39, v40, v37
	v_fma_f32 v36, -v36, v39, v38
	v_div_fmas_f32 v36, v36, v37, v39
	v_div_fixup_f32 v36, v36, v18, s23
	v_cmp_lt_f32_e32 vcc, 0, v18
	s_nop 1
	v_cndmask_b32_e32 v36, 0, v36, vcc
	v_mul_f32_e32 v12, v12, v36
	v_mul_f32_e32 v13, v13, v36
	v_mul_f32_e32 v14, v14, v36
	v_rndne_f32_e32 v12, v12
	v_rndne_f32_e32 v13, v13
	v_rndne_f32_e32 v14, v14
	v_mul_f32_e32 v15, v15, v36
	v_mul_f32_e32 v8, v8, v36
	v_mul_f32_e32 v11, v11, v36
	v_cvt_i32_f32_e32 v12, v12
	v_cvt_i32_f32_e32 v13, v13
	v_cvt_i32_f32_e32 v14, v14
	v_rndne_f32_e32 v15, v15
	v_rndne_f32_e32 v8, v8
	v_rndne_f32_e32 v11, v11
	v_cvt_i32_f32_e32 v15, v15
	v_cvt_i32_f32_e32 v8, v8
	v_cvt_i32_f32_e32 v11, v11
	v_med3_i32 v12, v12, -7, 7
	v_med3_i32 v13, v13, -7, 7
	v_med3_i32 v14, v14, -7, 7
	v_and_b32_e32 v12, 15, v12
	v_lshlrev_b32_e32 v13, 4, v13
	v_lshlrev_b32_e32 v14, 8, v14
	v_med3_i32 v15, v15, -7, 7
	v_mul_f32_e32 v9, v9, v36
	v_med3_i32 v8, v8, -7, 7
	v_mul_f32_e32 v10, v10, v36
	v_med3_i32 v11, v11, -7, 7
	v_and_b32_e32 v13, 0xf0, v13
	v_and_b32_e32 v14, 0xf00, v14
	v_lshlrev_b32_e32 v15, 12, v15
	v_rndne_f32_e32 v9, v9
	v_lshlrev_b32_e32 v8, 16, v8
	v_rndne_f32_e32 v10, v10
	v_lshl_or_b32 v11, v11, 28, v12
	v_mul_f32_e32 v4, v4, v36
	v_and_b32_e32 v15, 0xf000, v15
	v_cvt_i32_f32_e32 v9, v9
	v_and_b32_e32 v8, 0xf0000, v8
	v_cvt_i32_f32_e32 v10, v10
	v_or3_b32 v11, v11, v13, v14
	v_rndne_f32_e32 v4, v4
	v_or3_b32 v8, v11, v15, v8
	v_cvt_i32_f32_e32 v11, v4
	v_mul_f32_e32 v4, v5, v36
	v_mul_f32_e32 v6, v6, v36
	v_rndne_f32_e32 v4, v4
	v_rndne_f32_e32 v6, v6
	v_mul_f32_e32 v7, v7, v36
	v_mul_f32_e32 v0, v0, v36
	v_mul_f32_e32 v3, v3, v36
	v_cvt_i32_f32_e32 v5, v4
	v_cvt_i32_f32_e32 v6, v6
	v_rndne_f32_e32 v7, v7
	v_rndne_f32_e32 v0, v0
	v_mul_f32_e32 v1, v1, v36
	v_mul_f32_e32 v2, v2, v36
	v_rndne_f32_e32 v3, v3
	v_med3_i32 v9, v9, -7, 7
	v_med3_i32 v10, v10, -7, 7
	v_cvt_i32_f32_e32 v7, v7
	v_cvt_i32_f32_e32 v0, v0
	v_rndne_f32_e32 v1, v1
	v_rndne_f32_e32 v2, v2
	v_cvt_i32_f32_e32 v3, v3
	v_lshlrev_b32_e32 v9, 20, v9
	v_lshlrev_b32_e32 v10, 24, v10
	v_cvt_i32_f32_e32 v1, v1
	v_cvt_i32_f32_e32 v2, v2
	v_and_b32_e32 v9, 0xf00000, v9
	v_and_b32_e32 v10, 0xf000000, v10
	v_or3_b32 v4, v8, v9, v10
	v_med3_i32 v8, v11, -7, 7
	v_med3_i32 v5, v5, -7, 7
	v_med3_i32 v6, v6, -7, 7
	v_and_b32_e32 v8, 15, v8
	v_lshlrev_b32_e32 v5, 4, v5
	v_lshlrev_b32_e32 v6, 8, v6
	v_med3_i32 v7, v7, -7, 7
	v_med3_i32 v0, v0, -7, 7
	v_med3_i32 v3, v3, -7, 7
	v_and_b32_e32 v5, 0xf0, v5
	v_and_b32_e32 v6, 0xf00, v6
	v_lshlrev_b32_e32 v7, 12, v7
	v_lshlrev_b32_e32 v0, 16, v0
	v_med3_i32 v1, v1, -7, 7
	v_med3_i32 v2, v2, -7, 7
	v_lshl_or_b32 v3, v3, 28, v8
	v_and_b32_e32 v7, 0xf000, v7
	v_and_b32_e32 v0, 0xf0000, v0
	v_lshlrev_b32_e32 v1, 20, v1
	v_lshlrev_b32_e32 v2, 24, v2
	v_or3_b32 v3, v3, v5, v6
	v_and_b32_e32 v1, 0xf00000, v1
	v_and_b32_e32 v2, 0xf000000, v2
	v_or3_b32 v0, v3, v7, v0
	v_or3_b32 v5, v0, v1, v2
	global_store_dwordx2 v[22:23], v[4:5], off
	s_and_saveexec_b64 s[6:7], s[4:5]
	s_cbranch_execz .LBB0_797
	v_add_u32_e32 v0, s0, v17
	v_ashrrev_i32_e32 v1, 31, v0
	v_mul_f32_e32 v2, 0x3e124925, v18
	v_lshl_add_u64 v[0:1], v[0:1], 2, s[12:13]
	global_store_dword v[0:1], v2, off

; __device__ __forceinline__ float bf_lo(unsigned u) { return __uint_as_float(u << 16); }
; __device__ __forceinline__ float bf_hi(unsigned u) { return __uint_as_float(u & 0xffff0000u); }
; __device__ __forceinline__ int vblk() { return (int)blockIdx.x * 2 + half_id(); }
; __device__ __forceinline__ int vgrid() { return (int)gridDim.x * 2; }
; __device__ void phase_modnorm(const Params& p, const float* __restrict__ src, const bf16_t* __restrict__ srcb, const float* __restrict__ g, int shift_idx, int scale_idx, bf16_t* __restrict__ dst) {
;     ...
;     for (int tok = vblk() * 4 + wave; tok < NTOK; tok += vgrid() * 4) {
;         const int b = tok >> 11;
;         const float* xr = src + (size_t)tok * DM;
;         f32x4 v[4];
;         float ss = 0.f;
; #pragma unroll
;         for (int c = 0; c < 4; c++) {
;             if (srcb) {
;                 const u32x2 w = *(const u32x2*)(srcb + (size_t)tok * DM + c * 256 + lane * 4);
;                 v[c] = (f32x4){bf_lo(w.x), bf_hi(w.x), bf_lo(w.y), bf_hi(w.y)};
;             } else v[c] = *(const f32x4*)(xr + c * 256 + lane * 4);
;             ss += v[c][0] * v[c][0] + v[c][1] * v[c][1] + v[c][2] * v[c][2] + v[c][3] * v[c][3];
;         }
;         ss = wave_sum(ss);
;         const float rstd = rsqrtf(ss * (1.f / 1024.f) + 1e-6f);
; #pragma unroll
;         for (int c = 0; c < 4; c++) {
;             const int d = c * 256 + lane * 4;
;             const f32x4 gg = *(const f32x4*)(g + d);
;             const f32x4 sc = *(const f32x4*)(mod + b * 6144 + scale_idx * 1024 + d);
;             const f32x4 sh = *(const f32x4*)(mod + b * 6144 + shift_idx * 1024 + d);
;             float o[4];
; #pragma unroll
;             for (int j = 0; j < 4; j++) o[j] = (v[c][j] * rstd) * gg[j] * (1.f + sc[j]) + sh[j];
;             *(u32x2*)(dst + (size_t)tok * DM + d) = (u32x2){pack2(o[0], o[1]), pack2(o[2], o[3])};
;         }
;     }
.LBB0_854:
	global_load_dwordx2 v[66:67], v[20:21], off
	global_load_dwordx2 v[68:69], v[20:21], off offset:512
	global_load_dwordx2 v[70:71], v[20:21], off offset:1024
	global_load_dwordx2 v[72:73], v[20:21], off offset:1536
	v_ashrrev_i32_e32 v34, 11, v16
	v_mul_i32_i24_e32 v34, 0x1800, v34
	v_ashrrev_i32_e32 v35, 31, v34
	v_lshl_add_u64 v[34:35], v[34:35], 2, s[8:9]
	v_lshl_add_u64 v[36:37], v[34:35], 0, s[6:7]
	v_lshl_add_u64 v[34:35], v[34:35], 0, s[16:17]
	v_lshl_add_u64 v[78:79], v[36:37], 0, v[18:19]
	v_lshl_add_u64 v[80:81], v[34:35], 0, v[18:19]
	v_lshl_add_u64 v[82:83], v[36:37], 0, v[22:23]
	v_lshl_add_u64 v[84:85], v[34:35], 0, v[22:23]
	v_lshl_add_u64 v[86:87], v[36:37], 0, v[24:25]
	v_lshl_add_u64 v[88:89], v[34:35], 0, v[24:25]
	v_lshl_add_u64 v[90:91], v[36:37], 0, v[26:27]
	v_lshl_add_u64 v[92:93], v[34:35], 0, v[26:27]
	global_load_dwordx4 v[34:37], v[78:79], off
	global_load_dwordx4 v[38:41], v[82:83], off
	global_load_dwordx4 v[42:45], v[86:87], off
	global_load_dwordx4 v[46:49], v[90:91], off
	global_load_dwordx4 v[50:53], v[80:81], off
	global_load_dwordx4 v[54:57], v[84:85], off
	global_load_dwordx4 v[58:61], v[88:89], off
	global_load_dwordx4 v[62:65], v[92:93], off
	v_add_co_u32_e32 v74, vcc, s1, v20
	v_add_u32_e32 v16, s10, v16
	s_nop 0
	v_addc_co_u32_e32 v75, vcc, -1, v21, vcc
	v_add_co_u32_e32 v76, vcc, s2, v20
	s_waitcnt vmcnt(11)
	v_and_b32_e32 v81, 0xffff0000, v66
	s_waitcnt vmcnt(10)
	v_and_b32_e32 v83, 0xffff0000, v68
	v_lshlrev_b32_e32 v80, 16, v66
	v_lshlrev_b32_e32 v82, 16, v68
	s_waitcnt vmcnt(9)
	v_and_b32_e32 v85, 0xffff0000, v70
	s_waitcnt vmcnt(8)
	v_and_b32_e32 v87, 0xffff0000, v72
	v_mov_b32_e32 v92, v81
	v_mov_b32_e32 v93, v83
	v_lshlrev_b32_e32 v78, 16, v67
	v_lshlrev_b32_e32 v66, 16, v69
	v_lshlrev_b32_e32 v84, 16, v70
	v_lshlrev_b32_e32 v86, 16, v72
	v_mov_b32_e32 v90, v80
	v_mov_b32_e32 v91, v82
	v_mov_b32_e32 v100, v85
	v_mov_b32_e32 v101, v87
	v_pk_mul_f32 v[92:93], v[92:93], v[92:93]
	v_and_b32_e32 v79, 0xffff0000, v67
	v_and_b32_e32 v67, 0xffff0000, v69
	v_lshlrev_b32_e32 v68, 16, v71
	v_and_b32_e32 v69, 0xffff0000, v71
	v_lshlrev_b32_e32 v70, 16, v73
	v_and_b32_e32 v71, 0xffff0000, v73
	v_mov_b32_e32 v72, v78
	v_mov_b32_e32 v73, v66
	v_mov_b32_e32 v98, v84
	v_mov_b32_e32 v99, v86
	v_pk_mul_f32 v[100:101], v[100:101], v[100:101]
	v_pk_fma_f32 v[90:91], v[90:91], v[90:91], v[92:93]
	v_mov_b32_e32 v88, v79
	v_mov_b32_e32 v89, v67
	v_mov_b32_e32 v94, v68
	v_mov_b32_e32 v95, v70
	v_pk_fma_f32 v[92:93], v[98:99], v[98:99], v[100:101]
	v_pk_fma_f32 v[72:73], v[72:73], v[72:73], v[90:91]
	v_mov_b32_e32 v96, v69
	v_mov_b32_e32 v97, v71
	v_pk_fma_f32 v[90:91], v[94:95], v[94:95], v[92:93]
	v_pk_fma_f32 v[72:73], v[88:89], v[88:89], v[72:73]
	v_pk_fma_f32 v[88:89], v[96:97], v[96:97], v[90:91]
	v_add_f32_e32 v72, v72, v73
	v_add_f32_e32 v72, v72, v88
	v_add_f32_e32 v72, v72, v89
	s_nop 1
	v_add_f32_dpp v72, v72, v72 row_ror:8 row_mask:0xf bank_mask:0xf
	s_nop 1
	v_add_f32_dpp v72, v72, v72 row_ror:4 row_mask:0xf bank_mask:0xf
	s_nop 1
	v_add_f32_dpp v72, v72, v72 row_ror:2 row_mask:0xf bank_mask:0xf
	s_nop 1
	v_add_f32_dpp v72, v72, v72 row_ror:1 row_mask:0xf bank_mask:0xf
	v_mov_b32_e32 v73, v72
	s_nop 1
	v_permlane16_swap_b32_e32 v72, v73
	v_add_f32_e32 v72, v72, v73
	v_mov_b32_e32 v73, v72
	s_nop 1
	v_permlane32_swap_b32_e32 v72, v73
	v_add_f32_e32 v72, v72, v73
	v_addc_co_u32_e32 v77, vcc, -1, v21, vcc
	v_cmp_lt_i32_e32 vcc, s3, v16
	s_or_b64 s[14:15], vcc, s[14:15]
	s_waitcnt vmcnt(7)
	v_pk_add_f32 v[34:35], v[34:35], 1.0 op_sel_hi:[1,0]
	v_pk_add_f32 v[36:37], v[36:37], 1.0 op_sel_hi:[1,0]
	s_waitcnt vmcnt(6)
	v_pk_add_f32 v[38:39], v[38:39], 1.0 op_sel_hi:[1,0]
	v_pk_add_f32 v[40:41], v[40:41], 1.0 op_sel_hi:[1,0]
	s_waitcnt vmcnt(5)
	v_pk_add_f32 v[42:43], v[42:43], 1.0 op_sel_hi:[1,0]
	v_pk_add_f32 v[44:45], v[44:45], 1.0 op_sel_hi:[1,0]
	s_waitcnt vmcnt(4)
	v_pk_add_f32 v[46:47], v[46:47], 1.0 op_sel_hi:[1,0]
	v_pk_add_f32 v[48:49], v[48:49], 1.0 op_sel_hi:[1,0]
	v_lshl_add_u64 v[20:21], v[20:21], 0, s[12:13]
	v_fmamk_f32 v72, v72, 0x3a800000, v17
	v_mul_f32_e32 v73, 0x4b800000, v72
	v_cmp_gt_f32_e32 vcc, s0, v72
	s_nop 1
	v_cndmask_b32_e32 v72, v72, v73, vcc
	v_rsq_f32_e32 v72, v72
	s_nop 0
	v_mul_f32_e32 v73, 0x45800000, v72
	v_cndmask_b32_e32 v72, v72, v73, vcc
	v_pk_mul_f32 v[80:81], v[72:73], v[80:81] op_sel_hi:[0,1]
	v_pk_mul_f32 v[78:79], v[72:73], v[78:79] op_sel_hi:[0,1]
	v_pk_mul_f32 v[82:83], v[72:73], v[82:83] op_sel_hi:[0,1]
	v_pk_mul_f32 v[66:67], v[72:73], v[66:67] op_sel_hi:[0,1]
	v_pk_mul_f32 v[84:85], v[72:73], v[84:85] op_sel_hi:[0,1]
	v_pk_mul_f32 v[68:69], v[72:73], v[68:69] op_sel_hi:[0,1]
	v_pk_mul_f32 v[86:87], v[72:73], v[86:87] op_sel_hi:[0,1]
	v_pk_mul_f32 v[70:71], v[72:73], v[70:71] op_sel_hi:[0,1]
	v_pk_mul_f32 v[72:73], v[0:1], v[80:81]
	v_pk_mul_f32 v[78:79], v[2:3], v[78:79]
	v_pk_mul_f32 v[80:81], v[4:5], v[82:83]
	v_pk_mul_f32 v[66:67], v[6:7], v[66:67]
	v_pk_mul_f32 v[82:83], v[8:9], v[84:85]
	v_pk_mul_f32 v[68:69], v[10:11], v[68:69]
	v_pk_mul_f32 v[84:85], v[12:13], v[86:87]
	v_pk_mul_f32 v[70:71], v[14:15], v[70:71]
	s_waitcnt vmcnt(3)
	v_pk_fma_f32 v[34:35], v[34:35], v[72:73], v[50:51]
	v_pk_fma_f32 v[36:37], v[36:37], v[78:79], v[52:53]
	s_waitcnt vmcnt(2)
	v_pk_fma_f32 v[38:39], v[38:39], v[80:81], v[54:55]
	v_pk_fma_f32 v[40:41], v[40:41], v[66:67], v[56:57]
	s_waitcnt vmcnt(1)
	v_pk_fma_f32 v[42:43], v[42:43], v[82:83], v[58:59]
	v_pk_fma_f32 v[44:45], v[44:45], v[68:69], v[60:61]
	s_waitcnt vmcnt(0)
	v_pk_fma_f32 v[46:47], v[46:47], v[84:85], v[62:63]
	v_pk_fma_f32 v[48:49], v[48:49], v[70:71], v[64:65]
	v_cvt_pk_bf16_f32 v34, v34, v35
	v_cvt_pk_bf16_f32 v35, v36, v37
	v_cvt_pk_bf16_f32 v36, v38, v39
	v_cvt_pk_bf16_f32 v37, v40, v41
	v_cvt_pk_bf16_f32 v38, v42, v43
	v_cvt_pk_bf16_f32 v39, v44, v45
	v_cvt_pk_bf16_f32 v40, v46, v47
	v_cvt_pk_bf16_f32 v41, v48, v49
	global_store_dwordx2 v[74:75], v[34:35], off
	global_store_dwordx2 v[76:77], v[36:37], off offset:-3584
	global_store_dwordx2 v[76:77], v[38:39], off offset:-3072
	global_store_dwordx2 v[76:77], v[40:41], off offset:-2560
	s_andn2_b64 exec, exec, s[14:15]
	s_cbranch_execnz .LBB0_854
